# c38: in-proj output stores are write-through (sc1) so the release fence of the following grid barrier has little to write back
# speedup vs baseline: 1.0069x; 1.0069x over previous
; __device__ void gemm1_phase(const Params& p, int l, int hb, unsigned char* smem) {
;     ...
;         if (dbase) {
;             const int ch = lane & 7;
; #pragma unroll
;             for (int j = 0; j < 16; ++j) {
;                 const int rl = 8 * j + (lane >> 3), row = m0 + wm * 128 + rl;
;                 const u32x4 v = *(const u32x4*)(wl + rl * 128 + ((ch ^ (rl & 7)) * 16));
;                 size_t drow = (size_t)row;
;                 if (dsh >= 0) { const int bl = row >> 13, tt = row & (SEQ - 1); drow = (size_t)(bl * 3 + dg) * SEQ + (size_t)((tt & ((1 << dsh) - 1)) * (SEQ >> dsh) + (tt >> dsh)); }
;                 *(u32x4*)(dbase + drow * dpitch + dc0 + ch * 8) = v;
;             }
.LBB0_252:
	v_mul_lo_u32 v8, v7, s88
	v_mul_lo_u32 v9, v6, s89
	v_mad_u64_u32 v[6:7], s[16:17], v6, s88, 0
	v_add3_u32 v7, v7, v9, v8
	v_lshl_add_u64 v[4:5], v[6:7], 1, v[4:5]
	s_waitcnt lgkmcnt(0)
	global_store_dwordx4 v[4:5], v[0:3], off sc1

; __device__ void gemm1_phase(const Params& p, int l, int hb, unsigned char* smem) {
;     ...
;             if (cw == 8448) {
;                 float* dst = (float*)(p.ws + WS_DT);
;                 const f32x4 bias = *(const f32x4*)(p.dt_bias + l * 16 + lc);
; #pragma unroll
;                 for (int mi = 0; mi < 8; ++mi) {
;                     const int row = m0 + wm * 128 + mi * 16 + idx;
;                     f32x4 v = acc[mi][0] + bias, o;
;                     o.x = v.x > 20.f ? v.x : log1pf(__expf(v.x)); o.y = v.y > 20.f ? v.y : log1pf(__expf(v.y));
;                     o.z = v.z > 20.f ? v.z : log1pf(__expf(v.z)); o.w = v.w > 20.f ? v.w : log1pf(__expf(v.w));
;                     *(f32x4*)(dst + (size_t)row * 16 + lc) = o;
;                 }
.LBB0_472:
	s_or_b64 exec, exec, s[36:37]
	s_lshl_b32 s9, s57, 7
	s_add_i32 s9, s9, s56
	v_or_b32_e32 v140, s9, v231
	v_readlane_b32 s16, v255, 52
	v_readlane_b32 s17, v255, 53
	v_ashrrev_i32_e32 v141, 31, v140
	v_lshlrev_b64 v[142:143], 6, v[140:141]
	v_lshl_add_u64 v[138:139], s[16:17], 0, v[80:81]
	v_lshl_add_u64 v[142:143], v[138:139], 0, v[142:143]
	global_store_dwordx4 v[142:143], v[134:137], off sc1
	s_nop 1
	v_pk_add_f32 v[134:135], v[110:111], v[130:131]
	s_nop 0
	v_cmp_nlt_f32_e32 vcc, s12, v134
	s_and_saveexec_b64 s[36:37], vcc
	s_cbranch_execz .LBB0_474
	v_mul_f32_e32 v80, 0x3fb8aa3b, v134
	v_exp_f32_e32 v80, v80
	s_nop 0
	v_add_f32_e32 v134, 1.0, v80
	v_frexp_mant_f32_e32 v142, v134
	v_cvt_f64_f32_e32 v[136:137], v134
	v_add_f32_e32 v141, -1.0, v134
	v_frexp_exp_i32_f64_e32 v136, v[136:137]
	v_cmp_gt_f32_e32 vcc, s18, v142
	v_sub_f32_e32 v143, v141, v134
	v_sub_f32_e32 v141, v80, v141
	v_subbrev_co_u32_e32 v148, vcc, 0, v136, vcc
	v_add_f32_e32 v143, 1.0, v143
	v_sub_u32_e32 v136, 0, v148
	v_add_f32_e32 v141, v141, v143
	v_ldexp_f32 v134, v134, v136
	v_ldexp_f32 v136, v141, v136
	v_add_f32_e32 v141, -1.0, v134
	v_add_f32_e32 v137, 1.0, v141
	v_sub_f32_e32 v137, v134, v137
	v_add_f32_e32 v142, v136, v137
	v_add_f32_e32 v137, 1.0, v134
	v_add_f32_e32 v143, -1.0, v137
	v_sub_f32_e32 v134, v134, v143
	v_add_f32_e32 v134, v136, v134
	v_add_f32_e32 v149, v137, v134
	v_rcp_f32_e32 v150, v149
	v_sub_f32_e32 v136, v149, v137
	v_add_f32_e32 v137, v141, v142
	v_sub_f32_e32 v134, v134, v136
	v_sub_f32_e32 v136, v137, v141
	v_mul_f32_e32 v151, v137, v150
	v_sub_f32_e32 v141, v142, v136
	v_mul_f32_e32 v142, v149, v151
	v_fma_f32 v144, v151, v149, -v142
	v_fmac_f32_e32 v144, v151, v134
	v_add_f32_e32 v136, v142, v144
	v_sub_f32_e32 v143, v137, v136
	v_pk_add_f32 v[146:147], v[136:137], v[142:143] neg_lo:[0,1] neg_hi:[0,1]
	v_mov_b32_e32 v145, v136
	v_pk_add_f32 v[136:137], v[146:147], v[144:145] neg_lo:[0,1] neg_hi:[0,1]
	v_cmp_neq_f32_e32 vcc, s20, v80
	v_add_f32_e32 v137, v141, v137
	v_add_f32_e32 v136, v136, v137
	v_add_f32_e32 v137, v143, v136
	v_mul_f32_e32 v141, v150, v137
	v_mul_f32_e32 v142, v149, v141
	v_fma_f32 v144, v141, v149, -v142
	v_fmac_f32_e32 v144, v141, v134
	v_sub_f32_e32 v134, v143, v137
	v_add_f32_e32 v134, v136, v134
	v_add_f32_e32 v136, v142, v144
	v_sub_f32_e32 v143, v137, v136
	v_pk_add_f32 v[146:147], v[136:137], v[142:143] neg_lo:[0,1] neg_hi:[0,1]
	v_mov_b32_e32 v145, v136
	v_pk_add_f32 v[136:137], v[146:147], v[144:145] neg_lo:[0,1] neg_hi:[0,1]
	s_nop 0
	v_add_f32_e32 v134, v134, v137
	v_add_f32_e32 v134, v136, v134
	v_add_f32_e32 v137, v151, v141
	v_add_f32_e32 v134, v143, v134
	v_sub_f32_e32 v136, v137, v151
	v_mul_f32_e32 v134, v150, v134
	v_sub_f32_e32 v136, v141, v136
	v_add_f32_e32 v134, v136, v134
	v_add_f32_e32 v141, v137, v134
	v_mul_f32_e32 v142, v141, v141
	v_fmamk_f32 v136, v142, 0x3e9b6dac, v215
	v_fmaak_f32 v179, v142, v136, 0x3f2aaada
	v_cvt_f32_i32_e32 v136, v148
	v_sub_f32_e32 v137, v141, v137
	v_sub_f32_e32 v134, v134, v137
	v_mul_f32_e32 v137, v141, v142
	v_pk_mul_f32 v[144:145], v[136:137], v[178:179]
	v_ldexp_f32 v143, v141, 1
	v_fma_f32 v142, v136, s19, -v144
	v_fmac_f32_e32 v142, 0xb102e308, v136
	v_pk_add_f32 v[136:137], v[144:145], v[142:143]
	v_ldexp_f32 v134, v134, 1
	v_sub_f32_e32 v141, v137, v143
	v_sub_f32_e32 v141, v145, v141
	v_add_f32_e32 v147, v134, v141
	v_mov_b32_e32 v146, v144
	v_pk_add_f32 v[144:145], v[136:137], v[144:145] neg_lo:[0,1] neg_hi:[0,1]
	v_pk_add_f32 v[148:149], v[136:137], v[146:147]
	v_mov_b32_e32 v143, v136
	v_mov_b32_e32 v145, v149
	v_pk_add_f32 v[150:151], v[142:143], v[144:145] neg_lo:[0,1] neg_hi:[0,1]
	v_pk_add_f32 v[142:143], v[142:143], v[144:145]
	v_mov_b32_e32 v146, v147
	v_pk_add_f32 v[144:145], v[142:143], v[136:137] op_sel:[1,0] op_sel_hi:[0,1] neg_lo:[0,1] neg_hi:[0,1]
	v_pk_add_f32 v[152:153], v[148:149], v[144:145] op_sel_hi:[1,0] neg_lo:[0,1] neg_hi:[0,1]
	v_mov_b32_e32 v148, v149
	v_mov_b32_e32 v149, v143
	v_pk_mov_b32 v[144:145], v[136:137], v[144:145] op_sel:[1,0]
	v_mov_b32_e32 v147, v136
	v_pk_add_f32 v[144:145], v[148:149], v[144:145] neg_lo:[0,1] neg_hi:[0,1]
	v_mov_b32_e32 v152, v150
	v_pk_add_f32 v[136:137], v[146:147], v[144:145] neg_lo:[0,1] neg_hi:[0,1]
	v_mov_b32_e32 v151, v143
	v_pk_add_f32 v[144:145], v[152:153], v[136:137]
	s_nop 0
	v_pk_add_f32 v[146:147], v[144:145], v[144:145] op_sel:[0,1] op_sel_hi:[1,0]
	s_nop 0
	v_pk_add_f32 v[142:143], v[142:143], v[146:147] op_sel:[1,0] op_sel_hi:[0,1]
	v_mov_b32_e32 v145, v142
	v_pk_add_f32 v[148:149], v[144:145], v[150:151] neg_lo:[0,1] neg_hi:[0,1]
	v_mov_b32_e32 v137, v146
	v_sub_f32_e32 v134, v144, v148
	v_pk_add_f32 v[136:137], v[136:137], v[148:149] neg_lo:[0,1] neg_hi:[0,1]
	v_sub_f32_e32 v134, v150, v134
	v_add_f32_e32 v134, v136, v134
	v_add_f32_e32 v134, v134, v137
	v_add_f32_e32 v134, v142, v134
	v_cndmask_b32_e32 v134, v224, v134, vcc
	v_cmp_ngt_f32_e32 vcc, -1.0, v80
	s_nop 1
	v_cndmask_b32_e32 v134, v225, v134, vcc
	v_cmp_neq_f32_e32 vcc, -1.0, v80
	s_nop 1
	v_cndmask_b32_e32 v134, v226, v134, vcc
	v_cmp_lt_f32_e64 vcc, |v80|, s21
	s_nop 1
	v_cndmask_b32_e32 v134, v134, v80, vcc

; __device__ void gemm1_phase(const Params& p, int l, int hb, unsigned char* smem) {
;     ...
;             if (cw == 8448) {
;                 float* dst = (float*)(p.ws + WS_DT);
;                 const f32x4 bias = *(const f32x4*)(p.dt_bias + l * 16 + lc);
; #pragma unroll
;                 for (int mi = 0; mi < 8; ++mi) {
;                     const int row = m0 + wm * 128 + mi * 16 + idx;
;                     f32x4 v = acc[mi][0] + bias, o;
;                     o.x = v.x > 20.f ? v.x : log1pf(__expf(v.x)); o.y = v.y > 20.f ? v.y : log1pf(__expf(v.y));
;                     o.z = v.z > 20.f ? v.z : log1pf(__expf(v.z)); o.w = v.w > 20.f ? v.w : log1pf(__expf(v.w));
;                     *(f32x4*)(dst + (size_t)row * 16 + lc) = o;
;                 }
.LBB0_478:
	s_or_b64 exec, exec, s[36:37]
	v_or_b32_e32 v142, 16, v140
	v_ashrrev_i32_e32 v143, 31, v142
	v_lshlrev_b64 v[142:143], 6, v[142:143]
	v_lshl_add_u64 v[142:143], v[138:139], 0, v[142:143]
	global_store_dwordx4 v[142:143], v[134:137], off sc1
	s_nop 1
	v_pk_add_f32 v[134:135], v[94:95], v[130:131]
	s_nop 0
	v_cmp_nlt_f32_e32 vcc, s12, v134
	s_and_saveexec_b64 s[36:37], vcc
	s_cbranch_execz .LBB0_480
	v_mul_f32_e32 v80, 0x3fb8aa3b, v134
	v_exp_f32_e32 v80, v80
	s_nop 0
	v_add_f32_e32 v134, 1.0, v80
	v_frexp_mant_f32_e32 v142, v134
	v_cvt_f64_f32_e32 v[136:137], v134
	v_add_f32_e32 v141, -1.0, v134
	v_frexp_exp_i32_f64_e32 v136, v[136:137]
	v_cmp_gt_f32_e32 vcc, s18, v142
	v_sub_f32_e32 v143, v141, v134
	v_sub_f32_e32 v141, v80, v141
	v_subbrev_co_u32_e32 v148, vcc, 0, v136, vcc
	v_add_f32_e32 v143, 1.0, v143
	v_sub_u32_e32 v136, 0, v148
	v_add_f32_e32 v141, v141, v143
	v_ldexp_f32 v134, v134, v136
	v_ldexp_f32 v136, v141, v136
	v_add_f32_e32 v141, -1.0, v134
	v_add_f32_e32 v137, 1.0, v141
	v_sub_f32_e32 v137, v134, v137
	v_add_f32_e32 v142, v136, v137
	v_add_f32_e32 v137, 1.0, v134
	v_add_f32_e32 v143, -1.0, v137
	v_sub_f32_e32 v134, v134, v143
	v_add_f32_e32 v134, v136, v134
	v_add_f32_e32 v149, v137, v134
	v_rcp_f32_e32 v150, v149
	v_sub_f32_e32 v136, v149, v137
	v_add_f32_e32 v137, v141, v142
	v_sub_f32_e32 v134, v134, v136
	v_sub_f32_e32 v136, v137, v141
	v_mul_f32_e32 v151, v137, v150
	v_sub_f32_e32 v141, v142, v136
	v_mul_f32_e32 v142, v149, v151
	v_fma_f32 v144, v151, v149, -v142
	v_fmac_f32_e32 v144, v151, v134
	v_add_f32_e32 v136, v142, v144
	v_sub_f32_e32 v143, v137, v136
	v_pk_add_f32 v[146:147], v[136:137], v[142:143] neg_lo:[0,1] neg_hi:[0,1]
	v_mov_b32_e32 v145, v136
	v_pk_add_f32 v[136:137], v[146:147], v[144:145] neg_lo:[0,1] neg_hi:[0,1]
	v_cmp_neq_f32_e32 vcc, s20, v80
	v_add_f32_e32 v137, v141, v137
	v_add_f32_e32 v136, v136, v137
	v_add_f32_e32 v137, v143, v136
	v_mul_f32_e32 v141, v150, v137
	v_mul_f32_e32 v142, v149, v141
	v_fma_f32 v144, v141, v149, -v142
	v_fmac_f32_e32 v144, v141, v134
	v_sub_f32_e32 v134, v143, v137
	v_add_f32_e32 v134, v136, v134
	v_add_f32_e32 v136, v142, v144
	v_sub_f32_e32 v143, v137, v136
	v_pk_add_f32 v[146:147], v[136:137], v[142:143] neg_lo:[0,1] neg_hi:[0,1]
	v_mov_b32_e32 v145, v136
	v_pk_add_f32 v[136:137], v[146:147], v[144:145] neg_lo:[0,1] neg_hi:[0,1]
	s_nop 0
	v_add_f32_e32 v134, v134, v137
	v_add_f32_e32 v134, v136, v134
	v_add_f32_e32 v137, v151, v141
	v_add_f32_e32 v134, v143, v134
	v_sub_f32_e32 v136, v137, v151
	v_mul_f32_e32 v134, v150, v134
	v_sub_f32_e32 v136, v141, v136
	v_add_f32_e32 v134, v136, v134
	v_add_f32_e32 v141, v137, v134
	v_mul_f32_e32 v142, v141, v141
	v_fmamk_f32 v136, v142, 0x3e9b6dac, v215
	v_fmaak_f32 v179, v142, v136, 0x3f2aaada
	v_cvt_f32_i32_e32 v136, v148
	v_sub_f32_e32 v137, v141, v137
	v_sub_f32_e32 v134, v134, v137
	v_mul_f32_e32 v137, v141, v142
	v_pk_mul_f32 v[144:145], v[136:137], v[178:179]
	v_ldexp_f32 v143, v141, 1
	v_fma_f32 v142, v136, s19, -v144
	v_fmac_f32_e32 v142, 0xb102e308, v136
	v_pk_add_f32 v[136:137], v[144:145], v[142:143]
	v_ldexp_f32 v134, v134, 1
	v_sub_f32_e32 v141, v137, v143
	v_sub_f32_e32 v141, v145, v141
	v_add_f32_e32 v147, v134, v141
	v_mov_b32_e32 v146, v144
	v_pk_add_f32 v[144:145], v[136:137], v[144:145] neg_lo:[0,1] neg_hi:[0,1]
	v_pk_add_f32 v[148:149], v[136:137], v[146:147]
	v_mov_b32_e32 v143, v136
	v_mov_b32_e32 v145, v149
	v_pk_add_f32 v[150:151], v[142:143], v[144:145] neg_lo:[0,1] neg_hi:[0,1]
	v_pk_add_f32 v[142:143], v[142:143], v[144:145]
	v_mov_b32_e32 v146, v147
	v_pk_add_f32 v[144:145], v[142:143], v[136:137] op_sel:[1,0] op_sel_hi:[0,1] neg_lo:[0,1] neg_hi:[0,1]
	v_pk_add_f32 v[152:153], v[148:149], v[144:145] op_sel_hi:[1,0] neg_lo:[0,1] neg_hi:[0,1]
	v_mov_b32_e32 v148, v149
	v_mov_b32_e32 v149, v143
	v_pk_mov_b32 v[144:145], v[136:137], v[144:145] op_sel:[1,0]
	v_mov_b32_e32 v147, v136
	v_pk_add_f32 v[144:145], v[148:149], v[144:145] neg_lo:[0,1] neg_hi:[0,1]
	v_mov_b32_e32 v152, v150
	v_pk_add_f32 v[136:137], v[146:147], v[144:145] neg_lo:[0,1] neg_hi:[0,1]
	v_mov_b32_e32 v151, v143
	v_pk_add_f32 v[144:145], v[152:153], v[136:137]
	s_nop 0
	v_pk_add_f32 v[146:147], v[144:145], v[144:145] op_sel:[0,1] op_sel_hi:[1,0]
	s_nop 0
	v_pk_add_f32 v[142:143], v[142:143], v[146:147] op_sel:[1,0] op_sel_hi:[0,1]
	v_mov_b32_e32 v145, v142
	v_pk_add_f32 v[148:149], v[144:145], v[150:151] neg_lo:[0,1] neg_hi:[0,1]
	v_mov_b32_e32 v137, v146
	v_sub_f32_e32 v134, v144, v148
	v_pk_add_f32 v[136:137], v[136:137], v[148:149] neg_lo:[0,1] neg_hi:[0,1]
	v_sub_f32_e32 v134, v150, v134
	v_add_f32_e32 v134, v136, v134
	v_add_f32_e32 v134, v134, v137
	v_add_f32_e32 v134, v142, v134
	v_cndmask_b32_e32 v134, v224, v134, vcc
	v_cmp_ngt_f32_e32 vcc, -1.0, v80
	s_nop 1
	v_cndmask_b32_e32 v134, v225, v134, vcc
	v_cmp_neq_f32_e32 vcc, -1.0, v80
	s_nop 1
	v_cndmask_b32_e32 v134, v226, v134, vcc
	v_cmp_lt_f32_e64 vcc, |v80|, s21
	s_nop 1
	v_cndmask_b32_e32 v134, v134, v80, vcc

; __device__ void gemm1_phase(const Params& p, int l, int hb, unsigned char* smem) {
;     ...
;             if (cw == 8448) {
;                 float* dst = (float*)(p.ws + WS_DT);
;                 const f32x4 bias = *(const f32x4*)(p.dt_bias + l * 16 + lc);
; #pragma unroll
;                 for (int mi = 0; mi < 8; ++mi) {
;                     const int row = m0 + wm * 128 + mi * 16 + idx;
;                     f32x4 v = acc[mi][0] + bias, o;
;                     o.x = v.x > 20.f ? v.x : log1pf(__expf(v.x)); o.y = v.y > 20.f ? v.y : log1pf(__expf(v.y));
;                     o.z = v.z > 20.f ? v.z : log1pf(__expf(v.z)); o.w = v.w > 20.f ? v.w : log1pf(__expf(v.w));
;                     *(f32x4*)(dst + (size_t)row * 16 + lc) = o;
;                 }
.LBB0_484:
	s_or_b64 exec, exec, s[36:37]
	v_or_b32_e32 v142, 32, v140
	v_ashrrev_i32_e32 v143, 31, v142
	v_lshlrev_b64 v[142:143], 6, v[142:143]
	v_lshl_add_u64 v[142:143], v[138:139], 0, v[142:143]
	global_store_dwordx4 v[142:143], v[134:137], off sc1
	s_nop 1
	v_pk_add_f32 v[134:135], v[76:77], v[130:131]
	s_nop 0
	v_cmp_nlt_f32_e32 vcc, s12, v134
	s_and_saveexec_b64 s[36:37], vcc
	s_cbranch_execz .LBB0_486
	v_mul_f32_e32 v80, 0x3fb8aa3b, v134
	v_exp_f32_e32 v80, v80
	s_nop 0
	v_add_f32_e32 v134, 1.0, v80
	v_frexp_mant_f32_e32 v142, v134
	v_cvt_f64_f32_e32 v[136:137], v134
	v_add_f32_e32 v141, -1.0, v134
	v_frexp_exp_i32_f64_e32 v136, v[136:137]
	v_cmp_gt_f32_e32 vcc, s18, v142
	v_sub_f32_e32 v143, v141, v134
	v_sub_f32_e32 v141, v80, v141
	v_subbrev_co_u32_e32 v148, vcc, 0, v136, vcc
	v_add_f32_e32 v143, 1.0, v143
	v_sub_u32_e32 v136, 0, v148
	v_add_f32_e32 v141, v141, v143
	v_ldexp_f32 v134, v134, v136
	v_ldexp_f32 v136, v141, v136
	v_add_f32_e32 v141, -1.0, v134
	v_add_f32_e32 v137, 1.0, v141
	v_sub_f32_e32 v137, v134, v137
	v_add_f32_e32 v142, v136, v137
	v_add_f32_e32 v137, 1.0, v134
	v_add_f32_e32 v143, -1.0, v137
	v_sub_f32_e32 v134, v134, v143
	v_add_f32_e32 v134, v136, v134
	v_add_f32_e32 v149, v137, v134
	v_rcp_f32_e32 v150, v149
	v_sub_f32_e32 v136, v149, v137
	v_add_f32_e32 v137, v141, v142
	v_sub_f32_e32 v134, v134, v136
	v_sub_f32_e32 v136, v137, v141
	v_mul_f32_e32 v151, v137, v150
	v_sub_f32_e32 v141, v142, v136
	v_mul_f32_e32 v142, v149, v151
	v_fma_f32 v144, v151, v149, -v142
	v_fmac_f32_e32 v144, v151, v134
	v_add_f32_e32 v136, v142, v144
	v_sub_f32_e32 v143, v137, v136
	v_pk_add_f32 v[146:147], v[136:137], v[142:143] neg_lo:[0,1] neg_hi:[0,1]
	v_mov_b32_e32 v145, v136
	v_pk_add_f32 v[136:137], v[146:147], v[144:145] neg_lo:[0,1] neg_hi:[0,1]
	v_cmp_neq_f32_e32 vcc, s20, v80
	v_add_f32_e32 v137, v141, v137
	v_add_f32_e32 v136, v136, v137
	v_add_f32_e32 v137, v143, v136
	v_mul_f32_e32 v141, v150, v137
	v_mul_f32_e32 v142, v149, v141
	v_fma_f32 v144, v141, v149, -v142
	v_fmac_f32_e32 v144, v141, v134
	v_sub_f32_e32 v134, v143, v137
	v_add_f32_e32 v134, v136, v134
	v_add_f32_e32 v136, v142, v144
	v_sub_f32_e32 v143, v137, v136
	v_pk_add_f32 v[146:147], v[136:137], v[142:143] neg_lo:[0,1] neg_hi:[0,1]
	v_mov_b32_e32 v145, v136
	v_pk_add_f32 v[136:137], v[146:147], v[144:145] neg_lo:[0,1] neg_hi:[0,1]
	s_nop 0
	v_add_f32_e32 v134, v134, v137
	v_add_f32_e32 v134, v136, v134
	v_add_f32_e32 v137, v151, v141
	v_add_f32_e32 v134, v143, v134
	v_sub_f32_e32 v136, v137, v151
	v_mul_f32_e32 v134, v150, v134
	v_sub_f32_e32 v136, v141, v136
	v_add_f32_e32 v134, v136, v134
	v_add_f32_e32 v141, v137, v134
	v_mul_f32_e32 v142, v141, v141
	v_fmamk_f32 v136, v142, 0x3e9b6dac, v215
	v_fmaak_f32 v179, v142, v136, 0x3f2aaada
	v_cvt_f32_i32_e32 v136, v148
	v_sub_f32_e32 v137, v141, v137
	v_sub_f32_e32 v134, v134, v137
	v_mul_f32_e32 v137, v141, v142
	v_pk_mul_f32 v[144:145], v[136:137], v[178:179]
	v_ldexp_f32 v143, v141, 1
	v_fma_f32 v142, v136, s19, -v144
	v_fmac_f32_e32 v142, 0xb102e308, v136
	v_pk_add_f32 v[136:137], v[144:145], v[142:143]
	v_ldexp_f32 v134, v134, 1
	v_sub_f32_e32 v141, v137, v143
	v_sub_f32_e32 v141, v145, v141
	v_add_f32_e32 v147, v134, v141
	v_mov_b32_e32 v146, v144
	v_pk_add_f32 v[144:145], v[136:137], v[144:145] neg_lo:[0,1] neg_hi:[0,1]
	v_pk_add_f32 v[148:149], v[136:137], v[146:147]
	v_mov_b32_e32 v143, v136
	v_mov_b32_e32 v145, v149
	v_pk_add_f32 v[150:151], v[142:143], v[144:145] neg_lo:[0,1] neg_hi:[0,1]
	v_pk_add_f32 v[142:143], v[142:143], v[144:145]
	v_mov_b32_e32 v146, v147
	v_pk_add_f32 v[144:145], v[142:143], v[136:137] op_sel:[1,0] op_sel_hi:[0,1] neg_lo:[0,1] neg_hi:[0,1]
	v_pk_add_f32 v[152:153], v[148:149], v[144:145] op_sel_hi:[1,0] neg_lo:[0,1] neg_hi:[0,1]
	v_mov_b32_e32 v148, v149
	v_mov_b32_e32 v149, v143
	v_pk_mov_b32 v[144:145], v[136:137], v[144:145] op_sel:[1,0]
	v_mov_b32_e32 v147, v136
	v_pk_add_f32 v[144:145], v[148:149], v[144:145] neg_lo:[0,1] neg_hi:[0,1]
	v_mov_b32_e32 v152, v150
	v_pk_add_f32 v[136:137], v[146:147], v[144:145] neg_lo:[0,1] neg_hi:[0,1]
	v_mov_b32_e32 v151, v143
	v_pk_add_f32 v[144:145], v[152:153], v[136:137]
	s_nop 0
	v_pk_add_f32 v[146:147], v[144:145], v[144:145] op_sel:[0,1] op_sel_hi:[1,0]
	s_nop 0
	v_pk_add_f32 v[142:143], v[142:143], v[146:147] op_sel:[1,0] op_sel_hi:[0,1]
	v_mov_b32_e32 v145, v142
	v_pk_add_f32 v[148:149], v[144:145], v[150:151] neg_lo:[0,1] neg_hi:[0,1]
	v_mov_b32_e32 v137, v146
	v_sub_f32_e32 v134, v144, v148
	v_pk_add_f32 v[136:137], v[136:137], v[148:149] neg_lo:[0,1] neg_hi:[0,1]
	v_sub_f32_e32 v134, v150, v134
	v_add_f32_e32 v134, v136, v134
	v_add_f32_e32 v134, v134, v137
	v_add_f32_e32 v134, v142, v134
	v_cndmask_b32_e32 v134, v224, v134, vcc
	v_cmp_ngt_f32_e32 vcc, -1.0, v80
	s_nop 1
	v_cndmask_b32_e32 v134, v225, v134, vcc
	v_cmp_neq_f32_e32 vcc, -1.0, v80
	s_nop 1
	v_cndmask_b32_e32 v134, v226, v134, vcc
	v_cmp_lt_f32_e64 vcc, |v80|, s21
	s_nop 1
	v_cndmask_b32_e32 v134, v134, v80, vcc

; __device__ void gemm1_phase(const Params& p, int l, int hb, unsigned char* smem) {
;     ...
;             if (cw == 8448) {
;                 float* dst = (float*)(p.ws + WS_DT);
;                 const f32x4 bias = *(const f32x4*)(p.dt_bias + l * 16 + lc);
; #pragma unroll
;                 for (int mi = 0; mi < 8; ++mi) {
;                     const int row = m0 + wm * 128 + mi * 16 + idx;
;                     f32x4 v = acc[mi][0] + bias, o;
;                     o.x = v.x > 20.f ? v.x : log1pf(__expf(v.x)); o.y = v.y > 20.f ? v.y : log1pf(__expf(v.y));
;                     o.z = v.z > 20.f ? v.z : log1pf(__expf(v.z)); o.w = v.w > 20.f ? v.w : log1pf(__expf(v.w));
;                     *(f32x4*)(dst + (size_t)row * 16 + lc) = o;
;                 }
.LBB0_490:
	s_or_b64 exec, exec, s[36:37]
	v_or_b32_e32 v142, 48, v140
	v_ashrrev_i32_e32 v143, 31, v142
	v_lshlrev_b64 v[142:143], 6, v[142:143]
	v_lshl_add_u64 v[142:143], v[138:139], 0, v[142:143]
	global_store_dwordx4 v[142:143], v[134:137], off sc1
	s_nop 1
	v_pk_add_f32 v[134:135], v[60:61], v[130:131]
	s_nop 0
	v_cmp_nlt_f32_e32 vcc, s12, v134
	s_and_saveexec_b64 s[36:37], vcc
	s_cbranch_execz .LBB0_492
	v_mul_f32_e32 v80, 0x3fb8aa3b, v134
	v_exp_f32_e32 v80, v80
	s_nop 0
	v_add_f32_e32 v134, 1.0, v80
	v_frexp_mant_f32_e32 v142, v134
	v_cvt_f64_f32_e32 v[136:137], v134
	v_add_f32_e32 v141, -1.0, v134
	v_frexp_exp_i32_f64_e32 v136, v[136:137]
	v_cmp_gt_f32_e32 vcc, s18, v142
	v_sub_f32_e32 v143, v141, v134
	v_sub_f32_e32 v141, v80, v141
	v_subbrev_co_u32_e32 v148, vcc, 0, v136, vcc
	v_add_f32_e32 v143, 1.0, v143
	v_sub_u32_e32 v136, 0, v148
	v_add_f32_e32 v141, v141, v143
	v_ldexp_f32 v134, v134, v136
	v_ldexp_f32 v136, v141, v136
	v_add_f32_e32 v141, -1.0, v134
	v_add_f32_e32 v137, 1.0, v141
	v_sub_f32_e32 v137, v134, v137
	v_add_f32_e32 v142, v136, v137
	v_add_f32_e32 v137, 1.0, v134
	v_add_f32_e32 v143, -1.0, v137
	v_sub_f32_e32 v134, v134, v143
	v_add_f32_e32 v134, v136, v134
	v_add_f32_e32 v149, v137, v134
	v_rcp_f32_e32 v150, v149
	v_sub_f32_e32 v136, v149, v137
	v_add_f32_e32 v137, v141, v142
	v_sub_f32_e32 v134, v134, v136
	v_sub_f32_e32 v136, v137, v141
	v_mul_f32_e32 v151, v137, v150
	v_sub_f32_e32 v141, v142, v136
	v_mul_f32_e32 v142, v149, v151
	v_fma_f32 v144, v151, v149, -v142
	v_fmac_f32_e32 v144, v151, v134
	v_add_f32_e32 v136, v142, v144
	v_sub_f32_e32 v143, v137, v136
	v_pk_add_f32 v[146:147], v[136:137], v[142:143] neg_lo:[0,1] neg_hi:[0,1]
	v_mov_b32_e32 v145, v136
	v_pk_add_f32 v[136:137], v[146:147], v[144:145] neg_lo:[0,1] neg_hi:[0,1]
	v_cmp_neq_f32_e32 vcc, s20, v80
	v_add_f32_e32 v137, v141, v137
	v_add_f32_e32 v136, v136, v137
	v_add_f32_e32 v137, v143, v136
	v_mul_f32_e32 v141, v150, v137
	v_mul_f32_e32 v142, v149, v141
	v_fma_f32 v144, v141, v149, -v142
	v_fmac_f32_e32 v144, v141, v134
	v_sub_f32_e32 v134, v143, v137
	v_add_f32_e32 v134, v136, v134
	v_add_f32_e32 v136, v142, v144
	v_sub_f32_e32 v143, v137, v136
	v_pk_add_f32 v[146:147], v[136:137], v[142:143] neg_lo:[0,1] neg_hi:[0,1]
	v_mov_b32_e32 v145, v136
	v_pk_add_f32 v[136:137], v[146:147], v[144:145] neg_lo:[0,1] neg_hi:[0,1]
	s_nop 0
	v_add_f32_e32 v134, v134, v137
	v_add_f32_e32 v134, v136, v134
	v_add_f32_e32 v137, v151, v141
	v_add_f32_e32 v134, v143, v134
	v_sub_f32_e32 v136, v137, v151
	v_mul_f32_e32 v134, v150, v134
	v_sub_f32_e32 v136, v141, v136
	v_add_f32_e32 v134, v136, v134
	v_add_f32_e32 v141, v137, v134
	v_mul_f32_e32 v142, v141, v141
	v_fmamk_f32 v136, v142, 0x3e9b6dac, v215
	v_fmaak_f32 v179, v142, v136, 0x3f2aaada
	v_cvt_f32_i32_e32 v136, v148
	v_sub_f32_e32 v137, v141, v137
	v_sub_f32_e32 v134, v134, v137
	v_mul_f32_e32 v137, v141, v142
	v_pk_mul_f32 v[144:145], v[136:137], v[178:179]
	v_ldexp_f32 v143, v141, 1
	v_fma_f32 v142, v136, s19, -v144
	v_fmac_f32_e32 v142, 0xb102e308, v136
	v_pk_add_f32 v[136:137], v[144:145], v[142:143]
	v_ldexp_f32 v134, v134, 1
	v_sub_f32_e32 v141, v137, v143
	v_sub_f32_e32 v141, v145, v141
	v_add_f32_e32 v147, v134, v141
	v_mov_b32_e32 v146, v144
	v_pk_add_f32 v[144:145], v[136:137], v[144:145] neg_lo:[0,1] neg_hi:[0,1]
	v_pk_add_f32 v[148:149], v[136:137], v[146:147]
	v_mov_b32_e32 v143, v136
	v_mov_b32_e32 v145, v149
	v_pk_add_f32 v[150:151], v[142:143], v[144:145] neg_lo:[0,1] neg_hi:[0,1]
	v_pk_add_f32 v[142:143], v[142:143], v[144:145]
	v_mov_b32_e32 v146, v147
	v_pk_add_f32 v[144:145], v[142:143], v[136:137] op_sel:[1,0] op_sel_hi:[0,1] neg_lo:[0,1] neg_hi:[0,1]
	v_pk_add_f32 v[152:153], v[148:149], v[144:145] op_sel_hi:[1,0] neg_lo:[0,1] neg_hi:[0,1]
	v_mov_b32_e32 v148, v149
	v_mov_b32_e32 v149, v143
	v_pk_mov_b32 v[144:145], v[136:137], v[144:145] op_sel:[1,0]
	v_mov_b32_e32 v147, v136
	v_pk_add_f32 v[144:145], v[148:149], v[144:145] neg_lo:[0,1] neg_hi:[0,1]
	v_mov_b32_e32 v152, v150
	v_pk_add_f32 v[136:137], v[146:147], v[144:145] neg_lo:[0,1] neg_hi:[0,1]
	v_mov_b32_e32 v151, v143
	v_pk_add_f32 v[144:145], v[152:153], v[136:137]
	s_nop 0
	v_pk_add_f32 v[146:147], v[144:145], v[144:145] op_sel:[0,1] op_sel_hi:[1,0]
	s_nop 0
	v_pk_add_f32 v[142:143], v[142:143], v[146:147] op_sel:[1,0] op_sel_hi:[0,1]
	v_mov_b32_e32 v145, v142
	v_pk_add_f32 v[148:149], v[144:145], v[150:151] neg_lo:[0,1] neg_hi:[0,1]
	v_mov_b32_e32 v137, v146
	v_sub_f32_e32 v134, v144, v148
	v_pk_add_f32 v[136:137], v[136:137], v[148:149] neg_lo:[0,1] neg_hi:[0,1]
	v_sub_f32_e32 v134, v150, v134
	v_add_f32_e32 v134, v136, v134
	v_add_f32_e32 v134, v134, v137
	v_add_f32_e32 v134, v142, v134
	v_cndmask_b32_e32 v134, v224, v134, vcc
	v_cmp_ngt_f32_e32 vcc, -1.0, v80
	s_nop 1
	v_cndmask_b32_e32 v134, v225, v134, vcc
	v_cmp_neq_f32_e32 vcc, -1.0, v80
	s_nop 1
	v_cndmask_b32_e32 v134, v226, v134, vcc
	v_cmp_lt_f32_e64 vcc, |v80|, s21
	s_nop 1
	v_cndmask_b32_e32 v134, v134, v80, vcc

; __device__ void gemm1_phase(const Params& p, int l, int hb, unsigned char* smem) {
;     ...
;             if (cw == 8448) {
;                 float* dst = (float*)(p.ws + WS_DT);
;                 const f32x4 bias = *(const f32x4*)(p.dt_bias + l * 16 + lc);
; #pragma unroll
;                 for (int mi = 0; mi < 8; ++mi) {
;                     const int row = m0 + wm * 128 + mi * 16 + idx;
;                     f32x4 v = acc[mi][0] + bias, o;
;                     o.x = v.x > 20.f ? v.x : log1pf(__expf(v.x)); o.y = v.y > 20.f ? v.y : log1pf(__expf(v.y));
;                     o.z = v.z > 20.f ? v.z : log1pf(__expf(v.z)); o.w = v.w > 20.f ? v.w : log1pf(__expf(v.w));
;                     *(f32x4*)(dst + (size_t)row * 16 + lc) = o;
;                 }
.LBB0_496:
	s_or_b64 exec, exec, s[36:37]
	v_or_b32_e32 v142, 64, v140
	v_ashrrev_i32_e32 v143, 31, v142
	v_lshlrev_b64 v[142:143], 6, v[142:143]
	v_lshl_add_u64 v[142:143], v[138:139], 0, v[142:143]
	global_store_dwordx4 v[142:143], v[134:137], off sc1
	s_nop 1
	v_pk_add_f32 v[134:135], v[44:45], v[130:131]
	s_nop 0
	v_cmp_nlt_f32_e32 vcc, s12, v134
	s_and_saveexec_b64 s[36:37], vcc
	s_cbranch_execz .LBB0_498
	v_mul_f32_e32 v80, 0x3fb8aa3b, v134
	v_exp_f32_e32 v80, v80
	s_nop 0
	v_add_f32_e32 v134, 1.0, v80
	v_frexp_mant_f32_e32 v142, v134
	v_cvt_f64_f32_e32 v[136:137], v134
	v_add_f32_e32 v141, -1.0, v134
	v_frexp_exp_i32_f64_e32 v136, v[136:137]
	v_cmp_gt_f32_e32 vcc, s18, v142
	v_sub_f32_e32 v143, v141, v134
	v_sub_f32_e32 v141, v80, v141
	v_subbrev_co_u32_e32 v148, vcc, 0, v136, vcc
	v_add_f32_e32 v143, 1.0, v143
	v_sub_u32_e32 v136, 0, v148
	v_add_f32_e32 v141, v141, v143
	v_ldexp_f32 v134, v134, v136
	v_ldexp_f32 v136, v141, v136
	v_add_f32_e32 v141, -1.0, v134
	v_add_f32_e32 v137, 1.0, v141
	v_sub_f32_e32 v137, v134, v137
	v_add_f32_e32 v142, v136, v137
	v_add_f32_e32 v137, 1.0, v134
	v_add_f32_e32 v143, -1.0, v137
	v_sub_f32_e32 v134, v134, v143
	v_add_f32_e32 v134, v136, v134
	v_add_f32_e32 v149, v137, v134
	v_rcp_f32_e32 v150, v149
	v_sub_f32_e32 v136, v149, v137
	v_add_f32_e32 v137, v141, v142
	v_sub_f32_e32 v134, v134, v136
	v_sub_f32_e32 v136, v137, v141
	v_mul_f32_e32 v151, v137, v150
	v_sub_f32_e32 v141, v142, v136
	v_mul_f32_e32 v142, v149, v151
	v_fma_f32 v144, v151, v149, -v142
	v_fmac_f32_e32 v144, v151, v134
	v_add_f32_e32 v136, v142, v144
	v_sub_f32_e32 v143, v137, v136
	v_pk_add_f32 v[146:147], v[136:137], v[142:143] neg_lo:[0,1] neg_hi:[0,1]
	v_mov_b32_e32 v145, v136
	v_pk_add_f32 v[136:137], v[146:147], v[144:145] neg_lo:[0,1] neg_hi:[0,1]
	v_cmp_neq_f32_e32 vcc, s20, v80
	v_add_f32_e32 v137, v141, v137
	v_add_f32_e32 v136, v136, v137
	v_add_f32_e32 v137, v143, v136
	v_mul_f32_e32 v141, v150, v137
	v_mul_f32_e32 v142, v149, v141
	v_fma_f32 v144, v141, v149, -v142
	v_fmac_f32_e32 v144, v141, v134
	v_sub_f32_e32 v134, v143, v137
	v_add_f32_e32 v134, v136, v134
	v_add_f32_e32 v136, v142, v144
	v_sub_f32_e32 v143, v137, v136
	v_pk_add_f32 v[146:147], v[136:137], v[142:143] neg_lo:[0,1] neg_hi:[0,1]
	v_mov_b32_e32 v145, v136
	v_pk_add_f32 v[136:137], v[146:147], v[144:145] neg_lo:[0,1] neg_hi:[0,1]
	s_nop 0
	v_add_f32_e32 v134, v134, v137
	v_add_f32_e32 v134, v136, v134
	v_add_f32_e32 v137, v151, v141
	v_add_f32_e32 v134, v143, v134
	v_sub_f32_e32 v136, v137, v151
	v_mul_f32_e32 v134, v150, v134
	v_sub_f32_e32 v136, v141, v136
	v_add_f32_e32 v134, v136, v134
	v_add_f32_e32 v141, v137, v134
	v_mul_f32_e32 v142, v141, v141
	v_fmamk_f32 v136, v142, 0x3e9b6dac, v215
	v_fmaak_f32 v179, v142, v136, 0x3f2aaada
	v_cvt_f32_i32_e32 v136, v148
	v_sub_f32_e32 v137, v141, v137
	v_sub_f32_e32 v134, v134, v137
	v_mul_f32_e32 v137, v141, v142
	v_pk_mul_f32 v[144:145], v[136:137], v[178:179]
	v_ldexp_f32 v143, v141, 1
	v_fma_f32 v142, v136, s19, -v144
	v_fmac_f32_e32 v142, 0xb102e308, v136
	v_pk_add_f32 v[136:137], v[144:145], v[142:143]
	v_ldexp_f32 v134, v134, 1
	v_sub_f32_e32 v141, v137, v143
	v_sub_f32_e32 v141, v145, v141
	v_add_f32_e32 v147, v134, v141
	v_mov_b32_e32 v146, v144
	v_pk_add_f32 v[144:145], v[136:137], v[144:145] neg_lo:[0,1] neg_hi:[0,1]
	v_pk_add_f32 v[148:149], v[136:137], v[146:147]
	v_mov_b32_e32 v143, v136
	v_mov_b32_e32 v145, v149
	v_pk_add_f32 v[150:151], v[142:143], v[144:145] neg_lo:[0,1] neg_hi:[0,1]
	v_pk_add_f32 v[142:143], v[142:143], v[144:145]
	v_mov_b32_e32 v146, v147
	v_pk_add_f32 v[144:145], v[142:143], v[136:137] op_sel:[1,0] op_sel_hi:[0,1] neg_lo:[0,1] neg_hi:[0,1]
	v_pk_add_f32 v[152:153], v[148:149], v[144:145] op_sel_hi:[1,0] neg_lo:[0,1] neg_hi:[0,1]
	v_mov_b32_e32 v148, v149
	v_mov_b32_e32 v149, v143
	v_pk_mov_b32 v[144:145], v[136:137], v[144:145] op_sel:[1,0]
	v_mov_b32_e32 v147, v136
	v_pk_add_f32 v[144:145], v[148:149], v[144:145] neg_lo:[0,1] neg_hi:[0,1]
	v_mov_b32_e32 v152, v150
	v_pk_add_f32 v[136:137], v[146:147], v[144:145] neg_lo:[0,1] neg_hi:[0,1]
	v_mov_b32_e32 v151, v143
	v_pk_add_f32 v[144:145], v[152:153], v[136:137]
	s_nop 0
	v_pk_add_f32 v[146:147], v[144:145], v[144:145] op_sel:[0,1] op_sel_hi:[1,0]
	s_nop 0
	v_pk_add_f32 v[142:143], v[142:143], v[146:147] op_sel:[1,0] op_sel_hi:[0,1]
	v_mov_b32_e32 v145, v142
	v_pk_add_f32 v[148:149], v[144:145], v[150:151] neg_lo:[0,1] neg_hi:[0,1]
	v_mov_b32_e32 v137, v146
	v_sub_f32_e32 v134, v144, v148
	v_pk_add_f32 v[136:137], v[136:137], v[148:149] neg_lo:[0,1] neg_hi:[0,1]
	v_sub_f32_e32 v134, v150, v134
	v_add_f32_e32 v134, v136, v134
	v_add_f32_e32 v134, v134, v137
	v_add_f32_e32 v134, v142, v134
	v_cndmask_b32_e32 v134, v224, v134, vcc
	v_cmp_ngt_f32_e32 vcc, -1.0, v80
	s_nop 1
	v_cndmask_b32_e32 v134, v225, v134, vcc
	v_cmp_neq_f32_e32 vcc, -1.0, v80
	s_nop 1
	v_cndmask_b32_e32 v134, v226, v134, vcc
	v_cmp_lt_f32_e64 vcc, |v80|, s21
	s_nop 1
	v_cndmask_b32_e32 v134, v134, v80, vcc

; __device__ void gemm1_phase(const Params& p, int l, int hb, unsigned char* smem) {
;     ...
;             if (cw == 8448) {
;                 float* dst = (float*)(p.ws + WS_DT);
;                 const f32x4 bias = *(const f32x4*)(p.dt_bias + l * 16 + lc);
; #pragma unroll
;                 for (int mi = 0; mi < 8; ++mi) {
;                     const int row = m0 + wm * 128 + mi * 16 + idx;
;                     f32x4 v = acc[mi][0] + bias, o;
;                     o.x = v.x > 20.f ? v.x : log1pf(__expf(v.x)); o.y = v.y > 20.f ? v.y : log1pf(__expf(v.y));
;                     o.z = v.z > 20.f ? v.z : log1pf(__expf(v.z)); o.w = v.w > 20.f ? v.w : log1pf(__expf(v.w));
;                     *(f32x4*)(dst + (size_t)row * 16 + lc) = o;
;                 }
.LBB0_502:
	s_or_b64 exec, exec, s[36:37]
	v_or_b32_e32 v142, 0x50, v140
	v_ashrrev_i32_e32 v143, 31, v142
	v_lshlrev_b64 v[142:143], 6, v[142:143]
	v_lshl_add_u64 v[142:143], v[138:139], 0, v[142:143]
	global_store_dwordx4 v[142:143], v[134:137], off sc1
	s_nop 1
	v_pk_add_f32 v[134:135], v[28:29], v[130:131]
	s_nop 0
	v_cmp_nlt_f32_e32 vcc, s12, v134
	s_and_saveexec_b64 s[36:37], vcc
	s_cbranch_execz .LBB0_504
	v_mul_f32_e32 v80, 0x3fb8aa3b, v134
	v_exp_f32_e32 v80, v80
	s_nop 0
	v_add_f32_e32 v134, 1.0, v80
	v_frexp_mant_f32_e32 v142, v134
	v_cvt_f64_f32_e32 v[136:137], v134
	v_add_f32_e32 v141, -1.0, v134
	v_frexp_exp_i32_f64_e32 v136, v[136:137]
	v_cmp_gt_f32_e32 vcc, s18, v142
	v_sub_f32_e32 v143, v141, v134
	v_sub_f32_e32 v141, v80, v141
	v_subbrev_co_u32_e32 v148, vcc, 0, v136, vcc
	v_add_f32_e32 v143, 1.0, v143
	v_sub_u32_e32 v136, 0, v148
	v_add_f32_e32 v141, v141, v143
	v_ldexp_f32 v134, v134, v136
	v_ldexp_f32 v136, v141, v136
	v_add_f32_e32 v141, -1.0, v134
	v_add_f32_e32 v137, 1.0, v141
	v_sub_f32_e32 v137, v134, v137
	v_add_f32_e32 v142, v136, v137
	v_add_f32_e32 v137, 1.0, v134
	v_add_f32_e32 v143, -1.0, v137
	v_sub_f32_e32 v134, v134, v143
	v_add_f32_e32 v134, v136, v134
	v_add_f32_e32 v149, v137, v134
	v_rcp_f32_e32 v150, v149
	v_sub_f32_e32 v136, v149, v137
	v_add_f32_e32 v137, v141, v142
	v_sub_f32_e32 v134, v134, v136
	v_sub_f32_e32 v136, v137, v141
	v_mul_f32_e32 v151, v137, v150
	v_sub_f32_e32 v141, v142, v136
	v_mul_f32_e32 v142, v149, v151
	v_fma_f32 v144, v151, v149, -v142
	v_fmac_f32_e32 v144, v151, v134
	v_add_f32_e32 v136, v142, v144
	v_sub_f32_e32 v143, v137, v136
	v_pk_add_f32 v[146:147], v[136:137], v[142:143] neg_lo:[0,1] neg_hi:[0,1]
	v_mov_b32_e32 v145, v136
	v_pk_add_f32 v[136:137], v[146:147], v[144:145] neg_lo:[0,1] neg_hi:[0,1]
	v_cmp_neq_f32_e32 vcc, s20, v80
	v_add_f32_e32 v137, v141, v137
	v_add_f32_e32 v136, v136, v137
	v_add_f32_e32 v137, v143, v136
	v_mul_f32_e32 v141, v150, v137
	v_mul_f32_e32 v142, v149, v141
	v_fma_f32 v144, v141, v149, -v142
	v_fmac_f32_e32 v144, v141, v134
	v_sub_f32_e32 v134, v143, v137
	v_add_f32_e32 v134, v136, v134
	v_add_f32_e32 v136, v142, v144
	v_sub_f32_e32 v143, v137, v136
	v_pk_add_f32 v[146:147], v[136:137], v[142:143] neg_lo:[0,1] neg_hi:[0,1]
	v_mov_b32_e32 v145, v136
	v_pk_add_f32 v[136:137], v[146:147], v[144:145] neg_lo:[0,1] neg_hi:[0,1]
	s_nop 0
	v_add_f32_e32 v134, v134, v137
	v_add_f32_e32 v134, v136, v134
	v_add_f32_e32 v137, v151, v141
	v_add_f32_e32 v134, v143, v134
	v_sub_f32_e32 v136, v137, v151
	v_mul_f32_e32 v134, v150, v134
	v_sub_f32_e32 v136, v141, v136
	v_add_f32_e32 v134, v136, v134
	v_add_f32_e32 v141, v137, v134
	v_mul_f32_e32 v142, v141, v141
	v_fmamk_f32 v136, v142, 0x3e9b6dac, v215
	v_fmaak_f32 v179, v142, v136, 0x3f2aaada
	v_cvt_f32_i32_e32 v136, v148
	v_sub_f32_e32 v137, v141, v137
	v_sub_f32_e32 v134, v134, v137
	v_mul_f32_e32 v137, v141, v142
	v_pk_mul_f32 v[144:145], v[136:137], v[178:179]
	v_ldexp_f32 v143, v141, 1
	v_fma_f32 v142, v136, s19, -v144
	v_fmac_f32_e32 v142, 0xb102e308, v136
	v_pk_add_f32 v[136:137], v[144:145], v[142:143]
	v_ldexp_f32 v134, v134, 1
	v_sub_f32_e32 v141, v137, v143
	v_sub_f32_e32 v141, v145, v141
	v_add_f32_e32 v147, v134, v141
	v_mov_b32_e32 v146, v144
	v_pk_add_f32 v[144:145], v[136:137], v[144:145] neg_lo:[0,1] neg_hi:[0,1]
	v_pk_add_f32 v[148:149], v[136:137], v[146:147]
	v_mov_b32_e32 v143, v136
	v_mov_b32_e32 v145, v149
	v_pk_add_f32 v[150:151], v[142:143], v[144:145] neg_lo:[0,1] neg_hi:[0,1]
	v_pk_add_f32 v[142:143], v[142:143], v[144:145]
	v_mov_b32_e32 v146, v147
	v_pk_add_f32 v[144:145], v[142:143], v[136:137] op_sel:[1,0] op_sel_hi:[0,1] neg_lo:[0,1] neg_hi:[0,1]
	v_pk_add_f32 v[152:153], v[148:149], v[144:145] op_sel_hi:[1,0] neg_lo:[0,1] neg_hi:[0,1]
	v_mov_b32_e32 v148, v149
	v_mov_b32_e32 v149, v143
	v_pk_mov_b32 v[144:145], v[136:137], v[144:145] op_sel:[1,0]
	v_mov_b32_e32 v147, v136
	v_pk_add_f32 v[144:145], v[148:149], v[144:145] neg_lo:[0,1] neg_hi:[0,1]
	v_mov_b32_e32 v152, v150
	v_pk_add_f32 v[136:137], v[146:147], v[144:145] neg_lo:[0,1] neg_hi:[0,1]
	v_mov_b32_e32 v151, v143
	v_pk_add_f32 v[144:145], v[152:153], v[136:137]
	s_nop 0
	v_pk_add_f32 v[146:147], v[144:145], v[144:145] op_sel:[0,1] op_sel_hi:[1,0]
	s_nop 0
	v_pk_add_f32 v[142:143], v[142:143], v[146:147] op_sel:[1,0] op_sel_hi:[0,1]
	v_mov_b32_e32 v145, v142
	v_pk_add_f32 v[148:149], v[144:145], v[150:151] neg_lo:[0,1] neg_hi:[0,1]
	v_mov_b32_e32 v137, v146
	v_sub_f32_e32 v134, v144, v148
	v_pk_add_f32 v[136:137], v[136:137], v[148:149] neg_lo:[0,1] neg_hi:[0,1]
	v_sub_f32_e32 v134, v150, v134
	v_add_f32_e32 v134, v136, v134
	v_add_f32_e32 v134, v134, v137
	v_add_f32_e32 v134, v142, v134
	v_cndmask_b32_e32 v134, v224, v134, vcc
	v_cmp_ngt_f32_e32 vcc, -1.0, v80
	s_nop 1
	v_cndmask_b32_e32 v134, v225, v134, vcc
	v_cmp_neq_f32_e32 vcc, -1.0, v80
	s_nop 1
	v_cndmask_b32_e32 v134, v226, v134, vcc
	v_cmp_lt_f32_e64 vcc, |v80|, s21
	s_nop 1
	v_cndmask_b32_e32 v134, v134, v80, vcc

; __device__ void gemm1_phase(const Params& p, int l, int hb, unsigned char* smem) {
;     ...
;             if (cw == 8448) {
;                 float* dst = (float*)(p.ws + WS_DT);
;                 const f32x4 bias = *(const f32x4*)(p.dt_bias + l * 16 + lc);
; #pragma unroll
;                 for (int mi = 0; mi < 8; ++mi) {
;                     const int row = m0 + wm * 128 + mi * 16 + idx;
;                     f32x4 v = acc[mi][0] + bias, o;
;                     o.x = v.x > 20.f ? v.x : log1pf(__expf(v.x)); o.y = v.y > 20.f ? v.y : log1pf(__expf(v.y));
;                     o.z = v.z > 20.f ? v.z : log1pf(__expf(v.z)); o.w = v.w > 20.f ? v.w : log1pf(__expf(v.w));
;                     *(f32x4*)(dst + (size_t)row * 16 + lc) = o;
;                 }
.LBB0_508:
	s_or_b64 exec, exec, s[36:37]
	v_or_b32_e32 v142, 0x60, v140
	v_ashrrev_i32_e32 v143, 31, v142
	v_lshlrev_b64 v[142:143], 6, v[142:143]
	v_pk_add_f32 v[130:131], v[12:13], v[130:131]
	v_lshl_add_u64 v[142:143], v[138:139], 0, v[142:143]
	v_cmp_nlt_f32_e32 vcc, s12, v130
	global_store_dwordx4 v[142:143], v[134:137], off sc1
	s_and_saveexec_b64 s[36:37], vcc
	s_cbranch_execz .LBB0_510
	v_mul_f32_e32 v80, 0x3fb8aa3b, v130
	v_exp_f32_e32 v80, v80
	s_nop 0
	v_add_f32_e32 v130, 1.0, v80
	v_add_f32_e32 v136, -1.0, v130
	v_frexp_mant_f32_e32 v137, v130
	v_cvt_f64_f32_e32 v[134:135], v130
	v_sub_f32_e32 v141, v136, v130
	v_sub_f32_e32 v136, v80, v136
	v_add_f32_e32 v141, 1.0, v141
	v_frexp_exp_i32_f64_e32 v134, v[134:135]
	v_cmp_gt_f32_e32 vcc, s18, v137
	v_add_f32_e32 v136, v136, v141
	s_nop 0
	v_subbrev_co_u32_e32 v141, vcc, 0, v134, vcc
	v_sub_u32_e32 v134, 0, v141
	v_ldexp_f32 v130, v130, v134
	v_ldexp_f32 v134, v136, v134
	v_add_f32_e32 v136, -1.0, v130
	v_add_f32_e32 v135, 1.0, v136
	v_sub_f32_e32 v135, v130, v135
	v_add_f32_e32 v137, v134, v135
	v_add_f32_e32 v135, 1.0, v130
	v_add_f32_e32 v142, -1.0, v135
	v_sub_f32_e32 v130, v130, v142
	v_add_f32_e32 v130, v134, v130
	v_add_f32_e32 v146, v135, v130
	v_rcp_f32_e32 v147, v146
	v_sub_f32_e32 v134, v146, v135
	v_add_f32_e32 v135, v136, v137
	v_sub_f32_e32 v130, v130, v134
	v_mul_f32_e32 v149, v135, v147
	v_sub_f32_e32 v134, v135, v136
	v_mul_f32_e32 v136, v146, v149
	v_fma_f32 v142, v149, v146, -v136
	v_fmac_f32_e32 v142, v149, v130
	v_sub_f32_e32 v148, v137, v134
	v_add_f32_e32 v134, v136, v142
	v_sub_f32_e32 v137, v135, v134
	v_pk_add_f32 v[144:145], v[134:135], v[136:137] neg_lo:[0,1] neg_hi:[0,1]
	v_mov_b32_e32 v143, v134
	v_pk_add_f32 v[134:135], v[144:145], v[142:143] neg_lo:[0,1] neg_hi:[0,1]
	v_cmp_neq_f32_e32 vcc, s20, v80
	v_add_f32_e32 v135, v148, v135
	v_add_f32_e32 v134, v134, v135
	v_add_f32_e32 v135, v137, v134
	v_mul_f32_e32 v148, v147, v135
	v_mul_f32_e32 v136, v146, v148
	v_fma_f32 v142, v148, v146, -v136
	v_fmac_f32_e32 v142, v148, v130
	v_sub_f32_e32 v130, v137, v135
	v_add_f32_e32 v130, v134, v130
	v_add_f32_e32 v134, v136, v142
	v_sub_f32_e32 v137, v135, v134
	v_pk_add_f32 v[144:145], v[134:135], v[136:137] neg_lo:[0,1] neg_hi:[0,1]
	v_mov_b32_e32 v143, v134
	v_pk_add_f32 v[134:135], v[144:145], v[142:143] neg_lo:[0,1] neg_hi:[0,1]
	s_nop 0
	v_add_f32_e32 v130, v130, v135
	v_add_f32_e32 v130, v134, v130
	v_add_f32_e32 v135, v149, v148
	v_add_f32_e32 v130, v137, v130
	v_sub_f32_e32 v134, v135, v149
	v_mul_f32_e32 v130, v147, v130
	v_sub_f32_e32 v134, v148, v134
	v_add_f32_e32 v130, v134, v130
	v_add_f32_e32 v136, v135, v130
	v_mul_f32_e32 v142, v136, v136
	v_fmamk_f32 v134, v142, 0x3e9b6dac, v215
	v_fmaak_f32 v179, v142, v134, 0x3f2aaada
	v_cvt_f32_i32_e32 v134, v141
	v_sub_f32_e32 v135, v136, v135
	v_sub_f32_e32 v130, v130, v135
	v_mul_f32_e32 v135, v136, v142
	v_pk_mul_f32 v[142:143], v[134:135], v[178:179]
	v_ldexp_f32 v137, v136, 1
	v_fma_f32 v136, v134, s19, -v142
	v_fmac_f32_e32 v136, 0xb102e308, v134
	v_pk_add_f32 v[134:135], v[142:143], v[136:137]
	v_ldexp_f32 v130, v130, 1
	v_sub_f32_e32 v137, v135, v137
	v_sub_f32_e32 v137, v143, v137
	v_add_f32_e32 v145, v130, v137
	v_mov_b32_e32 v144, v142
	v_pk_add_f32 v[142:143], v[134:135], v[142:143] neg_lo:[0,1] neg_hi:[0,1]
	v_pk_add_f32 v[146:147], v[134:135], v[144:145]
	v_mov_b32_e32 v137, v134
	v_mov_b32_e32 v143, v147
	v_pk_add_f32 v[148:149], v[136:137], v[142:143] neg_lo:[0,1] neg_hi:[0,1]
	v_pk_add_f32 v[136:137], v[136:137], v[142:143]
	v_mov_b32_e32 v144, v145
	v_pk_add_f32 v[142:143], v[136:137], v[134:135] op_sel:[1,0] op_sel_hi:[0,1] neg_lo:[0,1] neg_hi:[0,1]
	v_pk_add_f32 v[150:151], v[146:147], v[142:143] op_sel_hi:[1,0] neg_lo:[0,1] neg_hi:[0,1]
	v_mov_b32_e32 v146, v147
	v_mov_b32_e32 v147, v137
	v_pk_mov_b32 v[142:143], v[134:135], v[142:143] op_sel:[1,0]
	v_mov_b32_e32 v145, v134
	v_pk_add_f32 v[142:143], v[146:147], v[142:143] neg_lo:[0,1] neg_hi:[0,1]
	v_mov_b32_e32 v150, v148
	v_pk_add_f32 v[134:135], v[144:145], v[142:143] neg_lo:[0,1] neg_hi:[0,1]
	v_mov_b32_e32 v149, v137
	v_pk_add_f32 v[142:143], v[150:151], v[134:135]
	s_nop 0
	v_pk_add_f32 v[144:145], v[142:143], v[142:143] op_sel:[0,1] op_sel_hi:[1,0]
	s_nop 0
	v_pk_add_f32 v[136:137], v[136:137], v[144:145] op_sel:[1,0] op_sel_hi:[0,1]
	v_mov_b32_e32 v143, v136
	v_pk_add_f32 v[146:147], v[142:143], v[148:149] neg_lo:[0,1] neg_hi:[0,1]
	v_mov_b32_e32 v135, v144
	v_sub_f32_e32 v130, v142, v146
	v_pk_add_f32 v[134:135], v[134:135], v[146:147] neg_lo:[0,1] neg_hi:[0,1]
	v_sub_f32_e32 v130, v148, v130
	v_add_f32_e32 v130, v134, v130
	v_add_f32_e32 v130, v130, v135
	v_add_f32_e32 v130, v136, v130
	v_cndmask_b32_e32 v130, v224, v130, vcc
	v_cmp_ngt_f32_e32 vcc, -1.0, v80
	s_nop 1
	v_cndmask_b32_e32 v130, v225, v130, vcc
	v_cmp_neq_f32_e32 vcc, -1.0, v80
	s_nop 1
	v_cndmask_b32_e32 v130, v226, v130, vcc
	v_cmp_lt_f32_e64 vcc, |v80|, s21
	s_nop 1
	v_cndmask_b32_e32 v130, v130, v80, vcc

; __device__ void gemm1_phase(const Params& p, int l, int hb, unsigned char* smem) {
;     ...
; #pragma unroll
;                 for (int mi = 0; mi < 8; ++mi) {
;                     const int row = m0 + wm * 128 + mi * 16 + idx;
;                     f32x4 v = acc[mi][0] + bias, o;
;                     o.x = v.x > 20.f ? v.x : log1pf(__expf(v.x)); o.y = v.y > 20.f ? v.y : log1pf(__expf(v.y));
;                     o.z = v.z > 20.f ? v.z : log1pf(__expf(v.z)); o.w = v.w > 20.f ? v.w : log1pf(__expf(v.w));
;                     *(f32x4*)(dst + (size_t)row * 16 + lc) = o;
.LBB0_514:
	s_or_b64 exec, exec, s[36:37]
	v_or_b32_e32 v134, 0x70, v140
	v_ashrrev_i32_e32 v135, 31, v134
	v_lshlrev_b64 v[134:135], 6, v[134:135]
	v_lshl_add_u64 v[134:135], v[138:139], 0, v[134:135]
	global_store_dwordx4 v[134:135], v[130:133], off sc1

; __device__ void gemm1_phase(const Params& p, int l, int hb, unsigned char* smem) {
;     ...
;         if (dbase) {
;             const int ch = lane & 7;
; #pragma unroll
;             for (int j = 0; j < 16; ++j) {
;                 const int rl = 8 * j + (lane >> 3), row = m0 + wm * 128 + rl;
;                 const u32x4 v = *(const u32x4*)(wl + rl * 128 + ((ch ^ (rl & 7)) * 16));
;                 size_t drow = (size_t)row;
;                 if (dsh >= 0) { const int bl = row >> 13, tt = row & (SEQ - 1); drow = (size_t)(bl * 3 + dg) * SEQ + (size_t)((tt & ((1 << dsh) - 1)) * (SEQ >> dsh) + (tt >> dsh)); }
;                 *(u32x4*)(dbase + drow * dpitch + dc0 + ch * 8) = v;
;             }
.LBB0_524:
	s_ashr_i32 s59, s58, 31
	s_lshl_b64 s[16:17], s[58:59], 1
	s_add_u32 s16, s90, s16
	s_addc_u32 s17, s91, s17
	v_lshlrev_b32_e32 v80, 4, v179
	v_lshl_add_u64 v[4:5], s[16:17], 0, v[80:81]
	v_mul_lo_u32 v10, v7, s88
	v_mul_lo_u32 v11, v6, s89
	v_mad_u64_u32 v[6:7], s[16:17], v6, s88, 0
	v_add3_u32 v7, v7, v11, v10
	v_lshl_add_u64 v[6:7], v[6:7], 1, v[4:5]
	s_waitcnt lgkmcnt(0)
	global_store_dwordx4 v[6:7], v[0:3], off sc1
	v_cndmask_b32_e64 v7, 0, 1, s[56:57]
	v_cmp_ne_u32_e64 s[36:37], 1, v7
	v_or_b32_e32 v0, 8, v9
	v_or_b32_e32 v6, s12, v0
	v_lshl_add_u32 v0, v0, 7, v8
	ds_read_b128 v[0:3], v0
	s_andn2_b64 vcc, exec, s[56:57]
	v_ashrrev_i32_e32 v7, 31, v6
	s_cbranch_vccnz .LBB0_526
	v_and_b32_e32 v7, 0x1f8f, v6
	v_mov_b32_e32 v10, 0x1f8f
	v_bitop3_b32 v6, v6, s9, v10 bitop3:0x80
	v_lshrrev_b32_e32 v7, s50, v7
	v_mad_u32_u24 v80, v6, s11, v7
	v_lshl_add_u64 v[6:7], s[38:39], 0, v[80:81]
.LBB0_526:
	v_mul_lo_u32 v10, v7, s88
	v_mul_lo_u32 v11, v6, s89
	v_mad_u64_u32 v[6:7], s[16:17], v6, s88, 0
	v_add3_u32 v7, v7, v11, v10
	v_lshl_add_u64 v[6:7], v[6:7], 1, v[4:5]
	s_waitcnt lgkmcnt(0)
	global_store_dwordx4 v[6:7], v[0:3], off sc1
	s_and_b64 vcc, exec, s[36:37]
	s_nop 0
	v_or_b32_e32 v0, 16, v9
	v_or_b32_e32 v6, s12, v0
	v_lshl_add_u32 v0, v0, 7, v8
	ds_read_b128 v[0:3], v0
	v_ashrrev_i32_e32 v7, 31, v6
	s_cbranch_vccnz .LBB0_528
	v_and_b32_e32 v7, 0x1f97, v6
	v_mov_b32_e32 v10, 0x1f97
	v_bitop3_b32 v6, v6, s9, v10 bitop3:0x80
	v_lshrrev_b32_e32 v7, s50, v7
	v_mad_u32_u24 v80, v6, s11, v7
	v_lshl_add_u64 v[6:7], s[38:39], 0, v[80:81]
.LBB0_528:
	v_mul_lo_u32 v10, v7, s88
	v_mul_lo_u32 v11, v6, s89
	v_mad_u64_u32 v[6:7], s[16:17], v6, s88, 0
	v_add3_u32 v7, v7, v11, v10
	v_lshl_add_u64 v[6:7], v[6:7], 1, v[4:5]
	s_waitcnt lgkmcnt(0)
	global_store_dwordx4 v[6:7], v[0:3], off sc1
	s_and_b64 vcc, exec, s[36:37]
	s_nop 0
	v_or_b32_e32 v0, 24, v9
	v_or_b32_e32 v6, s12, v0
	v_lshl_add_u32 v0, v0, 7, v8
	ds_read_b128 v[0:3], v0
	v_ashrrev_i32_e32 v7, 31, v6
	s_cbranch_vccnz .LBB0_530
	v_and_b32_e32 v7, 0x1f9f, v6
	v_mov_b32_e32 v10, 0x1f9f
	v_bitop3_b32 v6, v6, s9, v10 bitop3:0x80
	v_lshrrev_b32_e32 v7, s50, v7
	v_mad_u32_u24 v80, v6, s11, v7
	v_lshl_add_u64 v[6:7], s[38:39], 0, v[80:81]
.LBB0_530:
	v_mul_lo_u32 v10, v7, s88
	v_mul_lo_u32 v11, v6, s89
	v_mad_u64_u32 v[6:7], s[16:17], v6, s88, 0
	v_add3_u32 v7, v7, v11, v10
	v_lshl_add_u64 v[6:7], v[6:7], 1, v[4:5]
	s_waitcnt lgkmcnt(0)
	global_store_dwordx4 v[6:7], v[0:3], off sc1
	s_and_b64 vcc, exec, s[36:37]
	s_nop 0
	v_or_b32_e32 v0, 32, v9
	v_or_b32_e32 v6, s12, v0
	v_lshl_add_u32 v0, v0, 7, v8
	ds_read_b128 v[0:3], v0
	v_ashrrev_i32_e32 v7, 31, v6
	s_cbranch_vccnz .LBB0_532
	v_and_b32_e32 v7, 0x1fa7, v6
	v_mov_b32_e32 v10, 0x1fa7
	v_bitop3_b32 v6, v6, s9, v10 bitop3:0x80
	v_lshrrev_b32_e32 v7, s50, v7
	v_mad_u32_u24 v80, v6, s11, v7
	v_lshl_add_u64 v[6:7], s[38:39], 0, v[80:81]
.LBB0_532:
	v_mul_lo_u32 v10, v7, s88
	v_mul_lo_u32 v11, v6, s89
	v_mad_u64_u32 v[6:7], s[16:17], v6, s88, 0
	v_add3_u32 v7, v7, v11, v10
	v_lshl_add_u64 v[6:7], v[6:7], 1, v[4:5]
	s_waitcnt lgkmcnt(0)
	global_store_dwordx4 v[6:7], v[0:3], off sc1
	s_and_b64 vcc, exec, s[36:37]
	s_nop 0
	v_or_b32_e32 v0, 40, v9
	v_or_b32_e32 v6, s12, v0
	v_lshl_add_u32 v0, v0, 7, v8
	ds_read_b128 v[0:3], v0
	v_ashrrev_i32_e32 v7, 31, v6
	s_cbranch_vccnz .LBB0_534
	v_and_b32_e32 v7, 0x1faf, v6
	v_mov_b32_e32 v10, 0x1faf
	v_bitop3_b32 v6, v6, s9, v10 bitop3:0x80
	v_lshrrev_b32_e32 v7, s50, v7
	v_mad_u32_u24 v80, v6, s11, v7
	v_lshl_add_u64 v[6:7], s[38:39], 0, v[80:81]
.LBB0_534:
	v_mul_lo_u32 v10, v7, s88
	v_mul_lo_u32 v11, v6, s89
	v_mad_u64_u32 v[6:7], s[16:17], v6, s88, 0
	v_add3_u32 v7, v7, v11, v10
	v_lshl_add_u64 v[6:7], v[6:7], 1, v[4:5]
	s_waitcnt lgkmcnt(0)
	global_store_dwordx4 v[6:7], v[0:3], off sc1
	s_and_b64 vcc, exec, s[36:37]
	s_nop 0
	v_or_b32_e32 v0, 48, v9
	v_or_b32_e32 v6, s12, v0
	v_lshl_add_u32 v0, v0, 7, v8
	ds_read_b128 v[0:3], v0
	v_ashrrev_i32_e32 v7, 31, v6
	s_cbranch_vccnz .LBB0_536
	v_and_b32_e32 v7, 0x1fb7, v6
	v_mov_b32_e32 v10, 0x1fb7
	v_bitop3_b32 v6, v6, s9, v10 bitop3:0x80
	v_lshrrev_b32_e32 v7, s50, v7
	v_mad_u32_u24 v80, v6, s11, v7
	v_lshl_add_u64 v[6:7], s[38:39], 0, v[80:81]
.LBB0_536:
	v_mul_lo_u32 v10, v7, s88
	v_mul_lo_u32 v11, v6, s89
	v_mad_u64_u32 v[6:7], s[16:17], v6, s88, 0
	v_add3_u32 v7, v7, v11, v10
	v_lshl_add_u64 v[6:7], v[6:7], 1, v[4:5]
	s_waitcnt lgkmcnt(0)
	global_store_dwordx4 v[6:7], v[0:3], off sc1
	s_and_b64 vcc, exec, s[36:37]
	s_nop 0
	v_or_b32_e32 v0, 56, v9
	v_or_b32_e32 v6, s12, v0
	v_lshl_add_u32 v0, v0, 7, v8
	ds_read_b128 v[0:3], v0
	v_ashrrev_i32_e32 v7, 31, v6
	s_cbranch_vccnz .LBB0_538
	v_and_b32_e32 v7, 0x1fbf, v6
	v_mov_b32_e32 v10, 0x1fbf
	v_bitop3_b32 v6, v6, s9, v10 bitop3:0x80
	v_lshrrev_b32_e32 v7, s50, v7
	v_mad_u32_u24 v80, v6, s11, v7
	v_lshl_add_u64 v[6:7], s[38:39], 0, v[80:81]
; __device__ void gemm1_phase(const Params& p, int l, int hb, unsigned char* smem) {
;     ...
;         if (dbase) {
;             const int ch = lane & 7;
; #pragma unroll
;             for (int j = 0; j < 16; ++j) {
;                 const int rl = 8 * j + (lane >> 3), row = m0 + wm * 128 + rl;
;                 const u32x4 v = *(const u32x4*)(wl + rl * 128 + ((ch ^ (rl & 7)) * 16));
;                 size_t drow = (size_t)row;
;                 if (dsh >= 0) { const int bl = row >> 13, tt = row & (SEQ - 1); drow = (size_t)(bl * 3 + dg) * SEQ + (size_t)((tt & ((1 << dsh) - 1)) * (SEQ >> dsh) + (tt >> dsh)); }
;                 *(u32x4*)(dbase + drow * dpitch + dc0 + ch * 8) = v;
;             }
.LBB0_538:
	v_mul_lo_u32 v10, v7, s88
	v_mul_lo_u32 v11, v6, s89
	v_mad_u64_u32 v[6:7], s[16:17], v6, s88, 0
	v_add3_u32 v7, v7, v11, v10
	v_lshl_add_u64 v[6:7], v[6:7], 1, v[4:5]
	s_waitcnt lgkmcnt(0)
	global_store_dwordx4 v[6:7], v[0:3], off sc1
	s_and_b64 vcc, exec, s[36:37]
	s_nop 0
	v_or_b32_e32 v0, 64, v9
	v_or_b32_e32 v6, s12, v0
	v_lshl_add_u32 v0, v0, 7, v8
	ds_read_b128 v[0:3], v0
	v_ashrrev_i32_e32 v7, 31, v6
	s_cbranch_vccnz .LBB0_540
	v_and_b32_e32 v7, 0x1fc7, v6
	v_mov_b32_e32 v10, 0x1fc7
	v_bitop3_b32 v6, v6, s9, v10 bitop3:0x80
	v_lshrrev_b32_e32 v7, s50, v7
	v_mad_u32_u24 v80, v6, s11, v7
	v_lshl_add_u64 v[6:7], s[38:39], 0, v[80:81]
.LBB0_540:
	v_mul_lo_u32 v10, v7, s88
	v_mul_lo_u32 v11, v6, s89
	v_mad_u64_u32 v[6:7], s[16:17], v6, s88, 0
	v_add3_u32 v7, v7, v11, v10
	v_lshl_add_u64 v[6:7], v[6:7], 1, v[4:5]
	s_waitcnt lgkmcnt(0)
	global_store_dwordx4 v[6:7], v[0:3], off sc1
	s_and_b64 vcc, exec, s[36:37]
	s_nop 0
	v_or_b32_e32 v0, 0x48, v9
	v_or_b32_e32 v6, s12, v0
	v_lshl_add_u32 v0, v0, 7, v8
	ds_read_b128 v[0:3], v0
	v_ashrrev_i32_e32 v7, 31, v6
	s_cbranch_vccnz .LBB0_542
	v_and_b32_e32 v7, 0x1fcf, v6
	v_mov_b32_e32 v10, 0x1fcf
	v_bitop3_b32 v6, v6, s9, v10 bitop3:0x80
	v_lshrrev_b32_e32 v7, s50, v7
	v_mad_u32_u24 v80, v6, s11, v7
	v_lshl_add_u64 v[6:7], s[38:39], 0, v[80:81]
.LBB0_542:
	v_mul_lo_u32 v10, v7, s88
	v_mul_lo_u32 v11, v6, s89
	v_mad_u64_u32 v[6:7], s[16:17], v6, s88, 0
	v_add3_u32 v7, v7, v11, v10
	v_lshl_add_u64 v[6:7], v[6:7], 1, v[4:5]
	s_waitcnt lgkmcnt(0)
	global_store_dwordx4 v[6:7], v[0:3], off sc1
	s_and_b64 vcc, exec, s[36:37]
	s_nop 0
	v_or_b32_e32 v0, 0x50, v9
	v_or_b32_e32 v6, s12, v0
	v_lshl_add_u32 v0, v0, 7, v8
	ds_read_b128 v[0:3], v0
	v_ashrrev_i32_e32 v7, 31, v6
	s_cbranch_vccnz .LBB0_544
	v_and_b32_e32 v7, 0x1fd7, v6
	v_mov_b32_e32 v10, 0x1fd7
	v_bitop3_b32 v6, v6, s9, v10 bitop3:0x80
	v_lshrrev_b32_e32 v7, s50, v7
	v_mad_u32_u24 v80, v6, s11, v7
	v_lshl_add_u64 v[6:7], s[38:39], 0, v[80:81]
.LBB0_544:
	v_mul_lo_u32 v10, v7, s88
	v_mul_lo_u32 v11, v6, s89
	v_mad_u64_u32 v[6:7], s[16:17], v6, s88, 0
	v_add3_u32 v7, v7, v11, v10
	v_lshl_add_u64 v[6:7], v[6:7], 1, v[4:5]
	s_waitcnt lgkmcnt(0)
	global_store_dwordx4 v[6:7], v[0:3], off sc1
	s_and_b64 vcc, exec, s[36:37]
	s_nop 0
	v_or_b32_e32 v0, 0x58, v9
	v_or_b32_e32 v6, s12, v0
	v_lshl_add_u32 v0, v0, 7, v8
	ds_read_b128 v[0:3], v0
	v_ashrrev_i32_e32 v7, 31, v6
	s_cbranch_vccnz .LBB0_546
	v_and_b32_e32 v7, 0x1fdf, v6
	v_mov_b32_e32 v10, 0x1fdf
	v_bitop3_b32 v6, v6, s9, v10 bitop3:0x80
	v_lshrrev_b32_e32 v7, s50, v7
	v_mad_u32_u24 v80, v6, s11, v7
	v_lshl_add_u64 v[6:7], s[38:39], 0, v[80:81]
.LBB0_546:
	v_mul_lo_u32 v10, v7, s88
	v_mul_lo_u32 v11, v6, s89
	v_mad_u64_u32 v[6:7], s[16:17], v6, s88, 0
	v_add3_u32 v7, v7, v11, v10
	v_lshl_add_u64 v[6:7], v[6:7], 1, v[4:5]
	s_waitcnt lgkmcnt(0)
	global_store_dwordx4 v[6:7], v[0:3], off sc1
	s_and_b64 vcc, exec, s[36:37]
	s_nop 0
	v_or_b32_e32 v0, 0x60, v9
	v_or_b32_e32 v6, s12, v0
	v_lshl_add_u32 v0, v0, 7, v8
	ds_read_b128 v[0:3], v0
	v_ashrrev_i32_e32 v7, 31, v6
	s_cbranch_vccnz .LBB0_548
	v_and_b32_e32 v7, 0x1fe7, v6
	v_mov_b32_e32 v10, 0x1fe7
	v_bitop3_b32 v6, v6, s9, v10 bitop3:0x80
	v_lshrrev_b32_e32 v7, s50, v7
	v_mad_u32_u24 v80, v6, s11, v7
	v_lshl_add_u64 v[6:7], s[38:39], 0, v[80:81]
.LBB0_548:
	v_mul_lo_u32 v10, v7, s88
	v_mul_lo_u32 v11, v6, s89
	v_mad_u64_u32 v[6:7], s[16:17], v6, s88, 0
	v_add3_u32 v7, v7, v11, v10
	v_lshl_add_u64 v[6:7], v[6:7], 1, v[4:5]
	s_waitcnt lgkmcnt(0)
	global_store_dwordx4 v[6:7], v[0:3], off sc1
	s_and_b64 vcc, exec, s[36:37]
	s_nop 0
	v_or_b32_e32 v0, 0x68, v9
	v_or_b32_e32 v6, s12, v0
	v_lshl_add_u32 v0, v0, 7, v8
	ds_read_b128 v[0:3], v0
	v_ashrrev_i32_e32 v7, 31, v6
	s_cbranch_vccnz .LBB0_550
	v_and_b32_e32 v7, 0x1fef, v6
	v_mov_b32_e32 v10, 0x1fef
	v_bitop3_b32 v6, v6, s9, v10 bitop3:0x80
	v_lshrrev_b32_e32 v7, s50, v7
	v_mad_u32_u24 v80, v6, s11, v7
	v_lshl_add_u64 v[6:7], s[38:39], 0, v[80:81]
.LBB0_550:
	v_mul_lo_u32 v10, v7, s88
	v_mul_lo_u32 v11, v6, s89
	v_mad_u64_u32 v[6:7], s[16:17], v6, s88, 0
	v_add3_u32 v7, v7, v11, v10
	v_lshl_add_u64 v[6:7], v[6:7], 1, v[4:5]
	s_waitcnt lgkmcnt(0)
	global_store_dwordx4 v[6:7], v[0:3], off sc1
	s_and_b64 vcc, exec, s[36:37]
	s_nop 0
	v_or_b32_e32 v0, 0x70, v9
	v_or_b32_e32 v6, s12, v0
	v_lshl_add_u32 v0, v0, 7, v8
	ds_read_b128 v[0:3], v0
	v_ashrrev_i32_e32 v7, 31, v6
	s_cbranch_vccnz .LBB0_552
	v_and_b32_e32 v7, 0x1ff7, v6
	v_mov_b32_e32 v10, 0x1ff7
	v_bitop3_b32 v6, v6, s9, v10 bitop3:0x80
	v_lshrrev_b32_e32 v7, s50, v7
	v_mad_u32_u24 v80, v6, s11, v7
	v_lshl_add_u64 v[6:7], s[38:39], 0, v[80:81]
.LBB0_552:
	v_mul_lo_u32 v10, v7, s88
	v_mul_lo_u32 v11, v6, s89
	v_mad_u64_u32 v[6:7], s[16:17], v6, s88, 0
	v_add3_u32 v7, v7, v11, v10
	v_lshl_add_u64 v[6:7], v[6:7], 1, v[4:5]
	s_waitcnt lgkmcnt(0)
	global_store_dwordx4 v[6:7], v[0:3], off sc1
	s_and_b64 vcc, exec, s[36:37]
	s_nop 0
	v_or_b32_e32 v0, 0x78, v9
	v_or_b32_e32 v6, s12, v0
	v_lshl_add_u32 v0, v0, 7, v8
	ds_read_b128 v[0:3], v0
	v_ashrrev_i32_e32 v7, 31, v6
	s_cbranch_vccnz .LBB0_252
	v_and_b32_e32 v7, 0x1fff, v6
	v_bitop3_b32 v6, v6, s9, v228 bitop3:0x80
	v_lshrrev_b32_e32 v7, s50, v7
	v_mad_u32_u24 v80, v6, s11, v7
	v_lshl_add_u64 v[6:7], s[38:39], 0, v[80:81]
	s_branch .LBB0_252
